# v69 + v_fmamk_f32 (VOP2 literal scale) instead of 3-reg v_fma_f32 in all softmax arg computations
# speedup vs baseline: 1.0067x; 1.0067x over previous
; #define LAS __attribute__((address_space(3)))
; #define MFMA(a, b, c) __builtin_amdgcn_mfma_f32_32x32x16_bf16((a), (b), (c), 0, 0, 0)
; template <int DVT>
; DI void attn_step(lptr sKw, int kpitch, lptr sV, int vpitch, const bf16x8 (&qf)[4], float& m, float& l, f32x16 (&O)[DVT],
;                   const LAS float* tb, bool far, float cfar, int lane) {
;     const int r = lane & 31, h = lane >> 5;
;     f32x16 p0, p1;
; #pragma unroll
;     for (int i = 0; i < 16; ++i) { p0[i] = 0.f; p1[i] = 0.f; }
;     bf16x8 kf[8];
; #pragma unroll
;     for (int s = 0; s < 4; ++s) {
;         kf[2 * s] = *(const LAS bf16x8*)(sKw + r * kpitch + (16 * s + 8 * h) * 2);
;         kf[2 * s + 1] = *(const LAS bf16x8*)(sKw + (32 + r) * kpitch + (16 * s + 8 * h) * 2);
;     }
;     __builtin_amdgcn_sched_barrier(0);
; #pragma unroll
;     for (int s = 0; s < 4; ++s) { p0 = MFMA(kf[2 * s], qf[s], p0); p1 = MFMA(kf[2 * s + 1], qf[s], p1); }
;     const int i16 = lane & 15, q = i16 >> 2, pp = i16 & 3, blk = (lane >> 4) & 1;
;     lptr vb = sV + (4 * h + q) * vpitch + (16 * blk + 4 * pp) * 2;
; DI void band_item(const Params& P, char* lds_blk, int layer, int bp) {
;     ...
;     for (int kt = kt0; kt < 4; ++kt) {
;         if (kt + 1 < 4) gload(kt + 1);
;         __syncthreads();
;         const int b = (kt - kt0) & 1;
;         const bool active = (64 * kt <= 128 + 32 * w + 31) && (64 * kt + 63 >= 128 + 32 * w - maxd);
;         if (active) {
;             const LAS float* tb = (const LAS float*)btab + (qpos - 64 * kt - 4 * h + 128 - 63);
;             lptr sK = (lptr)lds + b * (2 * 64 * GP);
;             attn_step<2>(sK, GP, sK + 64 * GP, GP, qf, m, l, O, tb, false, 0.f, lane);
.Lb3_noovr:
	s_add_i32 s0, s64, 63
	s_add_i32 s65, s65, 1
	v_cmp_le_u32_e32 vcc, s64, v126
	v_cmp_ge_u32_e64 s[0:1], s0, v128
	s_and_b32 s70, s65, 1
	s_and_b32 s70, s70, s101
	s_and_b64 s[72:73], vcc, s[0:1]
	s_waitcnt lgkmcnt(0)
	s_barrier
	s_and_saveexec_b64 s[0:1], s[72:73]
	s_cbranch_execz .LBB0_220
	s_mul_i32 s71, s70, 0x4800
	v_add_u32_e32 v98, s71, v125
	v_add3_u32 v38, v98, v127, v112
	v_add3_u32 v39, v98, v129, v112
	ds_read_b128 v[34:37], v38
	ds_read_b128 v[50:53], v38 offset:32
	ds_read_b128 v[54:57], v39
	ds_read_b128 v[136:139], v39 offset:32
	ds_read_b128 v[58:61], v38 offset:64
	ds_read_b128 v[62:65], v38 offset:96
	ds_read_b128 v[140:143], v39 offset:64
	ds_read_b128 v[144:147], v39 offset:96
	s_waitcnt lgkmcnt(0)
	v_mfma_f32_32x32x16_bf16 v[34:49], v[34:37], v[66:69], 0
	v_mfma_f32_32x32x16_bf16 v[34:49], v[50:53], v[70:73], v[34:49]
	v_add_u32_e32 v50, v98, v131
	v_add_u32_e32 v135, v50, v132
	ds_read_b64_tr_b16 v[102:103], v135 offset:9216
	ds_read_b64_tr_b16 v[104:105], v135 offset:10368
	ds_read_b64_tr_b16 v[100:101], v135 offset:10432
	ds_read_b64_tr_b16 v[98:99], v135 offset:9280
	v_mfma_f32_32x32x16_bf16 v[34:49], v[58:61], v[74:77], v[34:49]
	v_mfma_f32_32x32x16_bf16 v[34:49], v[62:65], v[78:81], v[34:49]
	v_mfma_f32_32x32x16_bf16 v[50:65], v[54:57], v[66:69], 0
	v_mfma_f32_32x32x16_bf16 v[50:65], v[136:139], v[70:73], v[50:65]
	ds_read2_b32 v[136:137], v134 offset0:58 offset1:59
	ds_read2_b32 v[138:139], v134 offset0:56 offset1:57
	ds_read2_b32 v[148:149], v134 offset0:50 offset1:51
	ds_read2_b32 v[150:151], v134 offset0:48 offset1:49
	ds_read2_b32 v[152:153], v134 offset0:26 offset1:27
	ds_read2_b32 v[154:155], v134 offset0:24 offset1:25
	ds_read2_b32 v[156:157], v134 offset0:18 offset1:19
	ds_read2_b32 v[158:159], v134 offset0:16 offset1:17
	v_mfma_f32_32x32x16_bf16 v[50:65], v[140:143], v[74:77], v[50:65]
	ds_read2_b32 v[140:141], v134 offset0:42 offset1:43
	ds_read2_b32 v[142:143], v134 offset0:40 offset1:41
	ds_read2_b32 v[160:161], v134 offset0:34 offset1:35
	ds_read2_b32 v[162:163], v134 offset0:32 offset1:33
	ds_read2_b32 v[164:165], v134 offset0:10 offset1:11
	ds_read2_b32 v[166:167], v134 offset0:8 offset1:9
	ds_read2_b32 v[168:169], v134 offset0:2 offset1:3
	ds_read2_b32 v[170:171], v134 offset1:1
	v_mfma_f32_32x32x16_bf16 v[50:65], v[144:147], v[78:81], v[50:65]
	s_nop 7
	s_nop 7
	s_nop 3
	s_waitcnt lgkmcnt(0)
	v_fmamk_f32 v137, v34, 0x3e38aa3b, v137
	v_fmamk_f32 v50, v50, 0x3e38aa3b, v153
	v_fmamk_f32 v35, v35, 0x3e38aa3b, v136
	v_fmamk_f32 v51, v51, 0x3e38aa3b, v152
	v_fmamk_f32 v36, v36, 0x3e38aa3b, v139
	v_fmamk_f32 v52, v52, 0x3e38aa3b, v155
	v_fmamk_f32 v37, v37, 0x3e38aa3b, v138
	v_fmamk_f32 v53, v53, 0x3e38aa3b, v154
	s_nop 0
	v_max3_f32 v34, v137, v35, v50
	v_fmamk_f32 v38, v38, 0x3e38aa3b, v149
	v_fmamk_f32 v39, v39, 0x3e38aa3b, v148
	v_fmamk_f32 v40, v40, 0x3e38aa3b, v151
	v_max3_f32 v136, v36, v37, v51
	v_fmamk_f32 v41, v41, 0x3e38aa3b, v150
	s_nop 0
	v_max3_f32 v34, v34, v52, v53
	v_fmamk_f32 v54, v54, 0x3e38aa3b, v157
	v_fmamk_f32 v55, v55, 0x3e38aa3b, v156
	v_fmamk_f32 v56, v56, 0x3e38aa3b, v159
	v_fmamk_f32 v57, v57, 0x3e38aa3b, v158
	v_max3_f32 v136, v136, v40, v41
	s_nop 0
	v_max3_f32 v34, v34, v38, v39
	v_fmamk_f32 v42, v42, 0x3e38aa3b, v141
	v_fmamk_f32 v43, v43, 0x3e38aa3b, v140
	v_fmamk_f32 v44, v44, 0x3e38aa3b, v143
	v_fmamk_f32 v45, v45, 0x3e38aa3b, v142
	v_max3_f32 v136, v136, v56, v57
	s_nop 0
	v_max3_f32 v34, v34, v54, v55
	v_fmamk_f32 v58, v58, 0x3e38aa3b, v165
	v_fmamk_f32 v59, v59, 0x3e38aa3b, v164
	v_fmamk_f32 v60, v60, 0x3e38aa3b, v167
	v_fmamk_f32 v61, v61, 0x3e38aa3b, v166
	v_max3_f32 v136, v136, v44, v45
	s_nop 0
	v_max3_f32 v34, v34, v42, v43
	v_fmamk_f32 v46, v46, 0x3e38aa3b, v161
	v_fmamk_f32 v47, v47, 0x3e38aa3b, v160
	v_fmamk_f32 v48, v48, 0x3e38aa3b, v163
	v_fmamk_f32 v49, v49, 0x3e38aa3b, v162
	v_max3_f32 v136, v136, v60, v61
	s_nop 0
	v_max3_f32 v34, v34, v58, v59
	v_fmamk_f32 v62, v62, 0x3e38aa3b, v169
	v_fmamk_f32 v63, v63, 0x3e38aa3b, v168
	v_fmamk_f32 v64, v64, 0x3e38aa3b, v171
	v_fmamk_f32 v65, v65, 0x3e38aa3b, v170
	v_max3_f32 v136, v136, v48, v49
	s_nop 0
	v_max3_f32 v34, v34, v46, v47
	s_nop 0
	v_max3_f32 v34, v34, v62, v63
	v_max3_f32 v136, v136, v64, v65
	s_nop 0
	v_max_f32_e32 v136, v136, v136
	v_max_f32_e32 v34, v34, v34
	v_max_f32_e32 v34, v34, v136
	v_mov_b32_e32 v136, v34
	s_nop 1
	v_permlane32_swap_b32_e32 v34, v136
	v_max_f32_e32 v136, v136, v136
	v_max_f32_e32 v34, v34, v34
	v_max_f32_e32 v34, v34, v136
	v_sub_f32_e32 v136, v34, v133
	v_cmp_lt_f32_e32 vcc, s45, v136
	v_max_f32_e32 v34, v133, v34
	s_nop 0
	v_cndmask_b32_e32 v34, v133, v34, vcc
	v_sub_f32 v136, v137, v34
	v_sub_f32 v50, v50, v34
	v_sub_f32 v51, v51, v34
	v_sub_f32 v36, v36, v34
	v_sub_f32 v52, v52, v34
	v_sub_f32 v53, v53, v34
	v_sub_f32 v54, v54, v34
	v_sub_f32 v39, v39, v34
	v_sub_f32 v55, v55, v34
	v_sub_f32 v40, v40, v34
	v_sub_f32 v56, v56, v34
	v_sub_f32 v57, v57, v34
	v_sub_f32 v58, v58, v34
	v_sub_f32 v43, v43, v34
	v_sub_f32 v44, v44, v34
	v_sub_f32 v47, v47, v34
	v_sub_f32 v48, v48, v34
	v_sub_f32 v137, v35, v34
	v_sub_f32 v138, v37, v34
	v_sub_f32 v139, v38, v34
	v_sub_f32 v140, v41, v34
	v_sub_f32 v141, v42, v34
	v_sub_f32 v142, v59, v34
	v_sub_f32 v143, v60, v34
	v_sub_f32 v144, v45, v34
	v_sub_f32 v145, v61, v34
	v_sub_f32 v146, v46, v34
	v_sub_f32 v147, v62, v34
	v_sub_f32 v148, v63, v34
	v_sub_f32 v149, v64, v34
	v_sub_f32 v150, v49, v34
	v_sub_f32 v151, v65, v34
	s_nop 0
	v_exp_f32_e32 v59, v136
	v_exp_f32_e32 v35, v50
	v_exp_f32_e32 v60, v137
	v_exp_f32_e32 v37, v51
	v_exp_f32_e32 v61, v36
	v_exp_f32_e32 v38, v52
	v_exp_f32_e32 v62, v138
	v_exp_f32_e32 v41, v53
	v_exp_f32_e32 v63, v139
	v_exp_f32_e32 v42, v54
	v_exp_f32_e32 v64, v39
	v_exp_f32_e32 v45, v55
	v_exp_f32_e32 v65, v40
	v_exp_f32_e32 v46, v56
	v_exp_f32_e32 v136, v140
	v_exp_f32_e32 v49, v57
	v_exp_f32_e32 v51, v141
	v_exp_f32_e32 v36, v58
	v_exp_f32_e32 v52, v43
	v_exp_f32_e32 v39, v142
	v_exp_f32_e32 v53, v44
	v_exp_f32_e32 v40, v143
	v_exp_f32_e32 v54, v144
	v_exp_f32_e32 v43, v145
	v_exp_f32_e32 v55, v146
	v_exp_f32_e32 v44, v147
	v_exp_f32_e32 v56, v47
	v_exp_f32_e32 v47, v148
	v_exp_f32_e32 v57, v48
	v_exp_f32_e32 v48, v149
	v_exp_f32_e32 v58, v150
	v_exp_f32_e32 v50, v151
	v_add_f32 v137, v59, v35
	v_add_f32 v138, v51, v36
	v_add_f32 v139, v52, v39
	v_add_f32 v140, v53, v40
	v_add_f32 v141, v54, v43
	v_add_f32 v142, v55, v44
	s_nop 1
	s_nop 0
	v_add_f32 v137, v137, v138
	v_add_f32 v138, v60, v37
	v_add_f32 v143, v56, v47
	v_add_f32 v144, v57, v48
	v_cmp_neq_f32_e32 vcc, v34, v133
	v_add_f32 v138, v138, v139
	v_add_f32 v139, v61, v38
	v_add_f32 v145, v58, v50
	s_nop 0
	v_add_f32 v139, v139, v140
	v_add_f32 v140, v62, v41
	v_add_f32 v137, v137, v138
	s_nop 0
	v_add_f32 v140, v140, v141
	v_add_f32 v141, v63, v42
	s_nop 0
	v_add_f32 v141, v141, v142
	v_add_f32 v142, v64, v45
	v_add_f32 v138, v139, v140
	s_nop 0
	v_add_f32 v142, v142, v143
	v_add_f32 v143, v65, v46
	v_add_f32 v137, v137, v138
	s_nop 0
	v_add_f32 v143, v143, v144
	v_add_f32 v144, v136, v49
	v_add_f32 v138, v141, v142
	s_nop 0
	v_add_f32 v144, v144, v145
	s_nop 0
	v_add_f32 v139, v143, v144
	s_nop 0
	v_add_f32 v138, v138, v139
	s_nop 0
	v_add_f32 v137, v137, v138
	s_cbranch_vccz .LBB0_219
	v_sub_f32_e32 v133, v133, v34
	v_exp_f32_e32 v138, v133
	s_nop 0
	v_mul_f32_e32 v124, v124, v138
	v_pk_mul_f32 v[32:33], v[32:33], v[138:139] op_sel_hi:[1,0]
	v_pk_mul_f32 v[30:31], v[30:31], v[138:139] op_sel_hi:[1,0]
	v_pk_mul_f32 v[28:29], v[28:29], v[138:139] op_sel_hi:[1,0]
	v_pk_mul_f32 v[26:27], v[26:27], v[138:139] op_sel_hi:[1,0]
	v_pk_mul_f32 v[24:25], v[24:25], v[138:139] op_sel_hi:[1,0]
	v_pk_mul_f32 v[22:23], v[22:23], v[138:139] op_sel_hi:[1,0]
	v_pk_mul_f32 v[20:21], v[20:21], v[138:139] op_sel_hi:[1,0]
	v_pk_mul_f32 v[18:19], v[18:19], v[138:139] op_sel_hi:[1,0]
	v_pk_mul_f32 v[16:17], v[16:17], v[138:139] op_sel_hi:[1,0]
	v_pk_mul_f32 v[14:15], v[14:15], v[138:139] op_sel_hi:[1,0]
	v_pk_mul_f32 v[12:13], v[12:13], v[138:139] op_sel_hi:[1,0]
	v_pk_mul_f32 v[10:11], v[10:11], v[138:139] op_sel_hi:[1,0]
	v_pk_mul_f32 v[8:9], v[8:9], v[138:139] op_sel_hi:[1,0]
	v_pk_mul_f32 v[6:7], v[6:7], v[138:139] op_sel_hi:[1,0]
	v_pk_mul_f32 v[4:5], v[4:5], v[138:139] op_sel_hi:[1,0]
	v_pk_mul_f32 v[2:3], v[2:3], v[138:139] op_sel_hi:[1,0]

; #define LAS __attribute__((address_space(3)))
; #define MFMA(a, b, c) __builtin_amdgcn_mfma_f32_32x32x16_bf16((a), (b), (c), 0, 0, 0)
; template <typename F>
; DI void diff_step(lptr sK, lptr sV, int kx0, int vl0, const bf16x8 (&qf)[4], float& m, float& l, f32x16 (&O)[4],
;                   const LAS float* tb, bool far, float cfar, int lane, F&& mid) {
;     ...
;     lptr kr = sK + r * 256;
;     bf16x8 kf[8];
; #pragma unroll
;     for (int s = 0; s < 4; ++s) {
;         const int co = (kx0 ^ (2 * s)) * 16;
;         kf[2 * s] = *(const LAS bf16x8*)(kr + co);
;         kf[2 * s + 1] = *(const LAS bf16x8*)(kr + 8192 + co);
;     }
;     __builtin_amdgcn_sched_barrier(0);
;     mid();
;     __builtin_amdgcn_sched_barrier(0);
; #pragma unroll
;     for (int s = 0; s < 4; ++s) { p0 = MFMA(kf[2 * s], qf[s], p0); p1 = MFMA(kf[2 * s + 1], qf[s], p1); }
;     ...
;     ATTN_TAIL(4, VADDR_SWZ)
.Ldu_A:
	s_waitcnt vmcnt(0)
	s_waitcnt lgkmcnt(0)
	s_barrier
	ds_read_b128 v[80:83], v14
	ds_read_b128 v[84:87], v14 offset:8192
	ds_read_b128 v[120:123], v15
	ds_read_b128 v[6:9], v15 offset:8192
	ds_read_b128 v[116:119], v221
	ds_read_b128 v[2:5], v221 offset:8192
	ds_read_b128 v[10:13], v222
	ds_read_b128 v[112:115], v222 offset:8192
	v_add_u32_e32 v220, 1, v220
	s_add_u32 s72, s63, 0x8000
	s_mov_b32 m0, s72
	s_nop 0
	global_load_lds_dwordx4 v170, s[64:65]
	s_add_u32 s72, s63, 0xc000
	s_mov_b32 m0, s72
	s_nop 0
	global_load_lds_dwordx4 v170, s[70:71]
	s_add_u32 s72, s63, 0x8400
	s_mov_b32 m0, s72
	s_nop 0
	global_load_lds_dwordx4 v172, s[64:65]
	s_add_u32 s72, s63, 0xc400
	s_mov_b32 m0, s72
	s_nop 0
	global_load_lds_dwordx4 v172, s[70:71]
	s_add_u32 s64, s64, 0xe0000
	s_addc_u32 s65, s65, 0
	s_add_u32 s70, s70, 0xe0000
	s_addc_u32 s71, s71, 0
	v_cmp_gt_i32_e32 vcc, s42, v217
	s_waitcnt lgkmcnt(7)
	v_mfma_f32_32x32x16_bf16 v[96:111], v[80:83], v[144:147], 0
	s_waitcnt lgkmcnt(6)
	v_mfma_f32_32x32x16_bf16 v[80:95], v[84:87], v[144:147], 0
	s_waitcnt lgkmcnt(5)
	v_mfma_f32_32x32x16_bf16 v[96:111], v[120:123], v[148:151], v[96:111]
	s_waitcnt lgkmcnt(4)
	v_mfma_f32_32x32x16_bf16 v[80:95], v[6:9], v[148:151], v[80:95]
	s_waitcnt lgkmcnt(3)
	v_mfma_f32_32x32x16_bf16 v[96:111], v[116:119], v[152:155], v[96:111]
	s_waitcnt lgkmcnt(2)
	v_mfma_f32_32x32x16_bf16 v[80:95], v[2:5], v[152:155], v[80:95]
	ds_read_b64_tr_b16 v[2:3], v199 offset:16384
	ds_read_b64_tr_b16 v[4:5], v210 offset:18432
	ds_read_b64_tr_b16 v[6:7], v211 offset:16384
	ds_read_b64_tr_b16 v[8:9], v212 offset:18432
	s_waitcnt lgkmcnt(5)
	v_mfma_f32_32x32x16_bf16 v[96:111], v[10:13], v[156:159], v[96:111]
	ds_read_b64_tr_b16 v[10:11], v213 offset:16384
	ds_read_b64_tr_b16 v[12:13], v214 offset:18432
	ds_read_b64_tr_b16 v[160:161], v215 offset:16384
	ds_read_b64_tr_b16 v[162:163], v216 offset:18432
	s_waitcnt lgkmcnt(8)
	v_mfma_f32_32x32x16_bf16 v[80:95], v[112:115], v[156:159], v[80:95]
	s_and_saveexec_b64 s[22:23], vcc
	s_xor_b64 s[22:23], exec, s[22:23]
	s_cbranch_execz .LBB0_258_a
	ds_read2_b32 v[112:113], v218 offset0:58 offset1:59
	ds_read2_b32 v[114:115], v218 offset0:56 offset1:57
	ds_read2_b32 v[116:117], v218 offset0:50 offset1:51
	ds_read2_b32 v[118:119], v218 offset0:48 offset1:49
	ds_read2_b32 v[120:121], v218 offset0:26 offset1:27
	ds_read2_b32 v[122:123], v218 offset0:24 offset1:25
	ds_read2_b32 v[124:125], v218 offset0:18 offset1:19
	ds_read2_b32 v[126:127], v218 offset0:16 offset1:17
	ds_read2_b32 v[128:129], v218 offset0:42 offset1:43
	ds_read2_b32 v[130:131], v218 offset0:40 offset1:41
	ds_read2_b32 v[132:133], v218 offset0:34 offset1:35
	ds_read2_b32 v[134:135], v218 offset0:32 offset1:33
	ds_read2_b32 v[136:137], v218 offset0:10 offset1:11
	ds_read2_b32 v[138:139], v218 offset0:8 offset1:9
	ds_read2_b32 v[140:141], v218 offset0:2 offset1:3
	ds_read2_b32 v[142:143], v218 offset1:1
	s_nop 7
	s_nop 7
	s_nop 3
	s_waitcnt lgkmcnt(14)
	v_fmamk_f32 v96, v96, 0x3e38aa3b, v113
	s_waitcnt lgkmcnt(11)
	v_fmamk_f32 v80, v80, 0x3e38aa3b, v121
	v_fmamk_f32 v97, v97, 0x3e38aa3b, v112
	v_fmamk_f32 v81, v81, 0x3e38aa3b, v120
	v_fmamk_f32 v98, v98, 0x3e38aa3b, v115
	s_waitcnt lgkmcnt(10)
	v_fmamk_f32 v82, v82, 0x3e38aa3b, v123
	v_fmamk_f32 v99, v99, 0x3e38aa3b, v114
	v_fmamk_f32 v83, v83, 0x3e38aa3b, v122
	v_max3_f32 v112, v96, v97, v80
	v_fmamk_f32 v100, v100, 0x3e38aa3b, v117
	v_fmamk_f32 v101, v101, 0x3e38aa3b, v116
	v_fmamk_f32 v102, v102, 0x3e38aa3b, v119
	s_nop 0
	v_max3_f32 v113, v98, v99, v81
	v_fmamk_f32 v103, v103, 0x3e38aa3b, v118
	v_max3_f32 v112, v112, v82, v83
	s_waitcnt lgkmcnt(9)
	v_fmamk_f32 v84, v84, 0x3e38aa3b, v125
	v_fmamk_f32 v85, v85, 0x3e38aa3b, v124
	s_waitcnt lgkmcnt(8)
	v_fmamk_f32 v86, v86, 0x3e38aa3b, v127
	v_fmamk_f32 v87, v87, 0x3e38aa3b, v126
	v_max3_f32 v113, v113, v102, v103
	v_max3_f32 v112, v112, v100, v101
	s_waitcnt lgkmcnt(7)
	v_fmamk_f32 v104, v104, 0x3e38aa3b, v129
	v_fmamk_f32 v105, v105, 0x3e38aa3b, v128
	s_waitcnt lgkmcnt(6)
	v_fmamk_f32 v106, v106, 0x3e38aa3b, v131
	v_fmamk_f32 v107, v107, 0x3e38aa3b, v130
	v_max3_f32 v113, v113, v86, v87
	v_max3_f32 v112, v112, v84, v85
	s_waitcnt lgkmcnt(3)
	v_fmamk_f32 v88, v88, 0x3e38aa3b, v137
	v_fmamk_f32 v89, v89, 0x3e38aa3b, v136
	s_waitcnt lgkmcnt(2)
	v_fmamk_f32 v90, v90, 0x3e38aa3b, v139
	v_fmamk_f32 v91, v91, 0x3e38aa3b, v138
	v_max3_f32 v113, v113, v106, v107
	v_max3_f32 v112, v112, v104, v105
	v_fmamk_f32 v108, v108, 0x3e38aa3b, v133
	v_fmamk_f32 v109, v109, 0x3e38aa3b, v132
	v_fmamk_f32 v110, v110, 0x3e38aa3b, v135
	v_fmamk_f32 v111, v111, 0x3e38aa3b, v134
	s_nop 0
	v_max3_f32 v113, v113, v90, v91
	v_max3_f32 v112, v112, v88, v89
	s_waitcnt lgkmcnt(1)
	v_fmamk_f32 v92, v92, 0x3e38aa3b, v141
	v_fmamk_f32 v93, v93, 0x3e38aa3b, v140
	s_waitcnt lgkmcnt(0)
	v_fmamk_f32 v94, v94, 0x3e38aa3b, v143
	v_fmamk_f32 v95, v95, 0x3e38aa3b, v142
	v_max3_f32 v113, v113, v110, v111
	v_max3_f32 v112, v112, v108, v109
	s_nop 0
	v_max3_f32 v112, v112, v92, v93
	v_max3_f32 v113, v113, v94, v95
	s_nop 0
	v_max_f32_e32 v113, v113, v113
	v_max_f32_e32 v112, v112, v112
	v_max_f32_e32 v112, v112, v113
	v_mov_b32_e32 v113, v112
	s_nop 1
	v_permlane32_swap_b32_e32 v112, v113
	v_max_f32_e32 v113, v113, v113
	v_max_f32_e32 v112, v112, v112
	v_max_f32_e32 v112, v112, v113
	v_sub_f32_e32 v113, v112, v226
	v_cmp_lt_f32_e32 vcc, s45, v113
	v_max_f32_e32 v112, v226, v112
	s_nop 0
	v_cndmask_b32_e32 v227, v226, v112, vcc
	v_sub_f32 v112, v96, v227
	v_sub_f32 v128, v80, v227
	v_sub_f32 v113, v97, v227
	v_sub_f32 v129, v81, v227
	v_sub_f32 v114, v98, v227
	v_sub_f32 v130, v82, v227
	v_sub_f32 v115, v99, v227
	v_sub_f32 v131, v83, v227
	v_sub_f32 v116, v100, v227
	v_sub_f32 v132, v84, v227
	v_sub_f32 v117, v101, v227
	v_sub_f32 v133, v85, v227
	v_sub_f32 v118, v102, v227
	v_sub_f32 v134, v86, v227
	v_sub_f32 v119, v103, v227
	v_sub_f32 v135, v87, v227
	v_sub_f32 v120, v104, v227
	v_sub_f32 v136, v88, v227
	v_sub_f32 v121, v105, v227
	v_sub_f32 v137, v89, v227
	v_sub_f32 v122, v106, v227
	v_sub_f32 v138, v90, v227
	v_sub_f32 v123, v107, v227
	v_sub_f32 v139, v91, v227
	v_sub_f32 v124, v108, v227
	v_sub_f32 v140, v92, v227
	v_sub_f32 v125, v109, v227
	v_sub_f32 v141, v93, v227
	v_sub_f32 v126, v110, v227
	v_sub_f32 v142, v94, v227
	v_sub_f32 v127, v111, v227
	v_sub_f32 v143, v95, v227
.LBB0_258_a:
	s_andn2_saveexec_b64 s[22:23], s[22:23]
	s_cbranch_execz .LBB0_260_a
	s_nop 7
	s_nop 7
	s_nop 3
	v_sub_f32_e32 v243, v198, v226
	v_max3_f32 v244, v96, v97, v80
	v_fmamk_f32 v112, v96, 0x3e38aa3b, v243
	v_fmamk_f32 v128, v80, 0x3e38aa3b, v243
	v_max3_f32 v245, v98, v99, v81
	v_fmamk_f32 v113, v97, 0x3e38aa3b, v243
	v_fmamk_f32 v129, v81, 0x3e38aa3b, v243
	v_max3_f32 v244, v244, v82, v83
	v_fmamk_f32 v114, v98, 0x3e38aa3b, v243
	v_fmamk_f32 v130, v82, 0x3e38aa3b, v243
	v_max3_f32 v245, v245, v102, v103
	v_fmamk_f32 v115, v99, 0x3e38aa3b, v243
	v_fmamk_f32 v131, v83, 0x3e38aa3b, v243
	v_max3_f32 v244, v244, v100, v101
	v_fmamk_f32 v116, v100, 0x3e38aa3b, v243
	v_fmamk_f32 v132, v84, 0x3e38aa3b, v243
	v_max3_f32 v245, v245, v86, v87
	v_fmamk_f32 v117, v101, 0x3e38aa3b, v243
	v_fmamk_f32 v133, v85, 0x3e38aa3b, v243
	v_max3_f32 v244, v244, v84, v85
	v_fmamk_f32 v118, v102, 0x3e38aa3b, v243
	v_fmamk_f32 v134, v86, 0x3e38aa3b, v243
	v_max3_f32 v245, v245, v106, v107
	v_fmamk_f32 v119, v103, 0x3e38aa3b, v243
	v_fmamk_f32 v135, v87, 0x3e38aa3b, v243
	v_max3_f32 v244, v244, v104, v105
	v_fmamk_f32 v120, v104, 0x3e38aa3b, v243
	v_fmamk_f32 v136, v88, 0x3e38aa3b, v243
	v_max3_f32 v245, v245, v90, v91
	v_fmamk_f32 v121, v105, 0x3e38aa3b, v243
	v_fmamk_f32 v137, v89, 0x3e38aa3b, v243
	v_max3_f32 v244, v244, v88, v89
	v_fmamk_f32 v122, v106, 0x3e38aa3b, v243
	v_fmamk_f32 v138, v90, 0x3e38aa3b, v243
	v_max3_f32 v245, v245, v110, v111
	v_fmamk_f32 v123, v107, 0x3e38aa3b, v243
	v_fmamk_f32 v139, v91, 0x3e38aa3b, v243
	v_max3_f32 v244, v244, v108, v109
	v_fmamk_f32 v124, v108, 0x3e38aa3b, v243
	v_fmamk_f32 v140, v92, 0x3e38aa3b, v243
	v_max3_f32 v245, v245, v94, v95
	v_fmamk_f32 v125, v109, 0x3e38aa3b, v243
	v_fmamk_f32 v141, v93, 0x3e38aa3b, v243
	v_max3_f32 v244, v244, v92, v93
	v_fmamk_f32 v126, v110, 0x3e38aa3b, v243
	v_fmamk_f32 v142, v94, 0x3e38aa3b, v243
	v_fmamk_f32 v127, v111, 0x3e38aa3b, v243
	v_fmamk_f32 v143, v95, 0x3e38aa3b, v243
	v_max_f32_e32 v244, v244, v245
	v_mov_b32_e32 v245, v244
	s_nop 1
	v_permlane32_swap_b32_e32 v244, v245
	v_max_f32_e32 v244, v244, v245
	v_fmamk_f32 v244, v244, 0x3e38aa3b, v198
	v_sub_f32_e32 v245, v244, v226
	v_cmp_lt_f32_e32 vcc, s45, v245
	v_max_f32_e32 v244, v226, v244
	s_nop 0
	v_cndmask_b32_e32 v227, v226, v244, vcc
	s_nop 2
	s_cbranch_vccz .Ldf_far_nofix_a
	v_sub_f32_e32 v243, v198, v227
	v_fmamk_f32 v112, v96, 0x3e38aa3b, v243
	v_fmamk_f32 v128, v80, 0x3e38aa3b, v243
	v_fmamk_f32 v113, v97, 0x3e38aa3b, v243
	v_fmamk_f32 v129, v81, 0x3e38aa3b, v243
	v_fmamk_f32 v114, v98, 0x3e38aa3b, v243
	v_fmamk_f32 v130, v82, 0x3e38aa3b, v243
	v_fmamk_f32 v115, v99, 0x3e38aa3b, v243
	v_fmamk_f32 v131, v83, 0x3e38aa3b, v243
	v_fmamk_f32 v116, v100, 0x3e38aa3b, v243
	v_fmamk_f32 v132, v84, 0x3e38aa3b, v243
	v_fmamk_f32 v117, v101, 0x3e38aa3b, v243
	v_fmamk_f32 v133, v85, 0x3e38aa3b, v243
	v_fmamk_f32 v118, v102, 0x3e38aa3b, v243
	v_fmamk_f32 v134, v86, 0x3e38aa3b, v243
	v_fmamk_f32 v119, v103, 0x3e38aa3b, v243
	v_fmamk_f32 v135, v87, 0x3e38aa3b, v243
	v_fmamk_f32 v120, v104, 0x3e38aa3b, v243
	v_fmamk_f32 v136, v88, 0x3e38aa3b, v243
	v_fmamk_f32 v121, v105, 0x3e38aa3b, v243
	v_fmamk_f32 v137, v89, 0x3e38aa3b, v243
	v_fmamk_f32 v122, v106, 0x3e38aa3b, v243
	v_fmamk_f32 v138, v90, 0x3e38aa3b, v243
	v_fmamk_f32 v123, v107, 0x3e38aa3b, v243
	v_fmamk_f32 v139, v91, 0x3e38aa3b, v243
	v_fmamk_f32 v124, v108, 0x3e38aa3b, v243
	v_fmamk_f32 v140, v92, 0x3e38aa3b, v243
	v_fmamk_f32 v125, v109, 0x3e38aa3b, v243
	v_fmamk_f32 v141, v93, 0x3e38aa3b, v243
	v_fmamk_f32 v126, v110, 0x3e38aa3b, v243
	v_fmamk_f32 v142, v94, 0x3e38aa3b, v243
	v_fmamk_f32 v127, v111, 0x3e38aa3b, v243
	v_fmamk_f32 v143, v95, 0x3e38aa3b, v243

; #define MFMA(a, b, c) __builtin_amdgcn_mfma_f32_32x32x16_bf16((a), (b), (c), 0, 0, 0)
; template <typename F>
; DI void diff_step(lptr sK, lptr sV, int kx0, int vl0, const bf16x8 (&qf)[4], float& m, float& l, f32x16 (&O)[4],
;                   const LAS float* tb, bool far, float cfar, int lane, F&& mid) {
;     ...
;     mid();
;     __builtin_amdgcn_sched_barrier(0);
; #pragma unroll
;     for (int s = 0; s < 4; ++s) { p0 = MFMA(kf[2 * s], qf[s], p0); p1 = MFMA(kf[2 * s + 1], qf[s], p1); }
;     ...
;     ATTN_TAIL(4, VADDR_SWZ)
.LBB0_256_b:
	s_or_b64 exec, exec, s[22:23]
	v_cmp_gt_i32_e32 vcc, s42, v217
	s_waitcnt lgkmcnt(7)
	v_mfma_f32_32x32x16_bf16 v[96:111], v[80:83], v[144:147], 0
	s_waitcnt lgkmcnt(6)
	v_mfma_f32_32x32x16_bf16 v[80:95], v[84:87], v[144:147], 0
	s_waitcnt lgkmcnt(5)
	v_mfma_f32_32x32x16_bf16 v[96:111], v[120:123], v[148:151], v[96:111]
	s_waitcnt lgkmcnt(4)
	v_mfma_f32_32x32x16_bf16 v[80:95], v[6:9], v[148:151], v[80:95]
	s_waitcnt lgkmcnt(3)
	v_mfma_f32_32x32x16_bf16 v[96:111], v[116:119], v[152:155], v[96:111]
	s_waitcnt lgkmcnt(2)
	v_mfma_f32_32x32x16_bf16 v[80:95], v[2:5], v[152:155], v[80:95]
	ds_read_b64_tr_b16 v[2:3], v199 offset:49152
	ds_read_b64_tr_b16 v[4:5], v210 offset:51200
	ds_read_b64_tr_b16 v[6:7], v211 offset:49152
	ds_read_b64_tr_b16 v[8:9], v212 offset:51200
	s_waitcnt lgkmcnt(5)
	v_mfma_f32_32x32x16_bf16 v[96:111], v[10:13], v[156:159], v[96:111]
	ds_read_b64_tr_b16 v[10:11], v213 offset:49152
	ds_read_b64_tr_b16 v[12:13], v214 offset:51200
	ds_read_b64_tr_b16 v[160:161], v215 offset:49152
	ds_read_b64_tr_b16 v[162:163], v216 offset:51200
	s_waitcnt lgkmcnt(8)
	v_mfma_f32_32x32x16_bf16 v[80:95], v[112:115], v[156:159], v[80:95]
	s_and_saveexec_b64 s[22:23], vcc
	s_xor_b64 s[22:23], exec, s[22:23]
	s_cbranch_execz .LBB0_258_b
	ds_read2_b32 v[112:113], v218 offset0:58 offset1:59
	ds_read2_b32 v[114:115], v218 offset0:56 offset1:57
	ds_read2_b32 v[116:117], v218 offset0:50 offset1:51
	ds_read2_b32 v[118:119], v218 offset0:48 offset1:49
	ds_read2_b32 v[120:121], v218 offset0:26 offset1:27
	ds_read2_b32 v[122:123], v218 offset0:24 offset1:25
	ds_read2_b32 v[124:125], v218 offset0:18 offset1:19
	ds_read2_b32 v[126:127], v218 offset0:16 offset1:17
	ds_read2_b32 v[128:129], v218 offset0:42 offset1:43
	ds_read2_b32 v[130:131], v218 offset0:40 offset1:41
	ds_read2_b32 v[132:133], v218 offset0:34 offset1:35
	ds_read2_b32 v[134:135], v218 offset0:32 offset1:33
	ds_read2_b32 v[136:137], v218 offset0:10 offset1:11
	ds_read2_b32 v[138:139], v218 offset0:8 offset1:9
	ds_read2_b32 v[140:141], v218 offset0:2 offset1:3
	ds_read2_b32 v[142:143], v218 offset1:1
	s_nop 7
	s_nop 7
	s_nop 3
	s_waitcnt lgkmcnt(14)
	v_fmamk_f32 v96, v96, 0x3e38aa3b, v113
	s_waitcnt lgkmcnt(11)
	v_fmamk_f32 v80, v80, 0x3e38aa3b, v121
	v_fmamk_f32 v97, v97, 0x3e38aa3b, v112
	v_fmamk_f32 v81, v81, 0x3e38aa3b, v120
	v_fmamk_f32 v98, v98, 0x3e38aa3b, v115
	s_waitcnt lgkmcnt(10)
	v_fmamk_f32 v82, v82, 0x3e38aa3b, v123
	v_fmamk_f32 v99, v99, 0x3e38aa3b, v114
	v_fmamk_f32 v83, v83, 0x3e38aa3b, v122
	v_max3_f32 v112, v96, v97, v80
	v_fmamk_f32 v100, v100, 0x3e38aa3b, v117
	v_fmamk_f32 v101, v101, 0x3e38aa3b, v116
	v_fmamk_f32 v102, v102, 0x3e38aa3b, v119
	s_nop 0
	v_max3_f32 v113, v98, v99, v81
	v_fmamk_f32 v103, v103, 0x3e38aa3b, v118
	v_max3_f32 v112, v112, v82, v83
	s_waitcnt lgkmcnt(9)
	v_fmamk_f32 v84, v84, 0x3e38aa3b, v125
	v_fmamk_f32 v85, v85, 0x3e38aa3b, v124
	s_waitcnt lgkmcnt(8)
	v_fmamk_f32 v86, v86, 0x3e38aa3b, v127
	v_fmamk_f32 v87, v87, 0x3e38aa3b, v126
	v_max3_f32 v113, v113, v102, v103
	v_max3_f32 v112, v112, v100, v101
	s_waitcnt lgkmcnt(7)
	v_fmamk_f32 v104, v104, 0x3e38aa3b, v129
	v_fmamk_f32 v105, v105, 0x3e38aa3b, v128
	s_waitcnt lgkmcnt(6)
	v_fmamk_f32 v106, v106, 0x3e38aa3b, v131
	v_fmamk_f32 v107, v107, 0x3e38aa3b, v130
	v_max3_f32 v113, v113, v86, v87
	v_max3_f32 v112, v112, v84, v85
	s_waitcnt lgkmcnt(3)
	v_fmamk_f32 v88, v88, 0x3e38aa3b, v137
	v_fmamk_f32 v89, v89, 0x3e38aa3b, v136
	s_waitcnt lgkmcnt(2)
	v_fmamk_f32 v90, v90, 0x3e38aa3b, v139
	v_fmamk_f32 v91, v91, 0x3e38aa3b, v138
	v_max3_f32 v113, v113, v106, v107
	v_max3_f32 v112, v112, v104, v105
	v_fmamk_f32 v108, v108, 0x3e38aa3b, v133
	v_fmamk_f32 v109, v109, 0x3e38aa3b, v132
	v_fmamk_f32 v110, v110, 0x3e38aa3b, v135
	v_fmamk_f32 v111, v111, 0x3e38aa3b, v134
	s_nop 0
	v_max3_f32 v113, v113, v90, v91
	v_max3_f32 v112, v112, v88, v89
	s_waitcnt lgkmcnt(1)
	v_fmamk_f32 v92, v92, 0x3e38aa3b, v141
	v_fmamk_f32 v93, v93, 0x3e38aa3b, v140
	s_waitcnt lgkmcnt(0)
	v_fmamk_f32 v94, v94, 0x3e38aa3b, v143
	v_fmamk_f32 v95, v95, 0x3e38aa3b, v142
	v_max3_f32 v113, v113, v110, v111
	v_max3_f32 v112, v112, v108, v109
	s_nop 0
	v_max3_f32 v112, v112, v92, v93
	v_max3_f32 v113, v113, v94, v95
	s_nop 0
	v_max_f32_e32 v113, v113, v113
	v_max_f32_e32 v112, v112, v112
	v_max_f32_e32 v112, v112, v113
	v_mov_b32_e32 v113, v112
	s_nop 1
	v_permlane32_swap_b32_e32 v112, v113
	v_max_f32_e32 v113, v113, v113
	v_max_f32_e32 v112, v112, v112
	v_max_f32_e32 v112, v112, v113
	v_sub_f32_e32 v113, v112, v226
	v_cmp_lt_f32_e32 vcc, s45, v113
	v_max_f32_e32 v112, v226, v112
	s_nop 0
	v_cndmask_b32_e32 v227, v226, v112, vcc
	v_sub_f32 v112, v96, v227
	v_sub_f32 v128, v80, v227
	v_sub_f32 v113, v97, v227
	v_sub_f32 v129, v81, v227
	v_sub_f32 v114, v98, v227
	v_sub_f32 v130, v82, v227
	v_sub_f32 v115, v99, v227
	v_sub_f32 v131, v83, v227
	v_sub_f32 v116, v100, v227
	v_sub_f32 v132, v84, v227
	v_sub_f32 v117, v101, v227
	v_sub_f32 v133, v85, v227
	v_sub_f32 v118, v102, v227
	v_sub_f32 v134, v86, v227
	v_sub_f32 v119, v103, v227
	v_sub_f32 v135, v87, v227
	v_sub_f32 v120, v104, v227
	v_sub_f32 v136, v88, v227
	v_sub_f32 v121, v105, v227
	v_sub_f32 v137, v89, v227
	v_sub_f32 v122, v106, v227
	v_sub_f32 v138, v90, v227
	v_sub_f32 v123, v107, v227
	v_sub_f32 v139, v91, v227
	v_sub_f32 v124, v108, v227
	v_sub_f32 v140, v92, v227
	v_sub_f32 v125, v109, v227
	v_sub_f32 v141, v93, v227
	v_sub_f32 v126, v110, v227
	v_sub_f32 v142, v94, v227
	v_sub_f32 v127, v111, v227
	v_sub_f32 v143, v95, v227
